# phase-0 adaLN GEMV: both halves of an 8-row step request their weight rows together (one memory round trip per step instead of two)
# speedup vs baseline: 1.0047x; 1.0046x over previous
; #define LAS __attribute__((address_space(3)))
; __global__ void __launch_bounds__(NWAVES * 64, 2) mk_fwd(Args args) {
;     ...
;                     const float* wp = args.in[9] + ((size_t)lm * DM + k0) * (3 * DM) + col;
; #pragma unroll 2
;                     for (int k = 0; k < 128; k += 4) {
;                         const f32x2 wa = *(const f32x2*)(wp + (size_t)(k + 0) * (3 * DM)), wb = *(const f32x2*)(wp + (size_t)(k + 1) * (3 * DM));
;                         const f32x2 wc = *(const f32x2*)(wp + (size_t)(k + 2) * (3 * DM)), wd = *(const f32x2*)(wp + (size_t)(k + 3) * (3 * DM));
; #pragma unroll
;                         for (int r2 = 0; r2 < 20; ++r2) { const f32x4 cv = *(LAS const f32x4*)(cs + r2 * 128 + k);
;                             acc[r2] = wa * cv.x + acc[r2]; acc[r2] = wb * cv.y + acc[r2]; acc[r2] = wc * cv.z + acc[r2]; acc[r2] = wd * cv.w + acc[r2]; }
.LBB0_29:
	s_mov_b32 s16, 0xfffac000
	v_add_co_u32_e32 v6, vcc, s16, v26
	s_mov_b32 s16, 0xfffb8000
	s_nop 0
	v_addc_co_u32_e32 v7, vcc, -1, v27, vcc
	global_load_dwordx2 v[68:69], v[6:7], off
	v_add_co_u32_e32 v6, vcc, s16, v26
	s_mov_b32 s16, 0xfffc4000
	s_nop 0
	v_addc_co_u32_e32 v7, vcc, -1, v27, vcc
	global_load_dwordx2 v[80:81], v[6:7], off
	v_add_co_u32_e32 v6, vcc, s16, v26
	s_mov_b32 s16, 0xfffd0000
	s_nop 0
	v_addc_co_u32_e32 v7, vcc, -1, v27, vcc
	global_load_dwordx2 v[82:83], v[6:7], off
	v_add_co_u32_e32 v6, vcc, s16, v26
	v_mov_b32_e32 v15, s1
	s_nop 0
	v_addc_co_u32_e32 v7, vcc, -1, v27, vcc
	global_load_dwordx2 v[84:85], v[6:7], off
	s_mov_b32 s16, 0xfffdc000
	v_add_co_u32_e32 v88, vcc, s16, v26
	s_mov_b32 s16, 0xfffe8000
	s_nop 0
	v_addc_co_u32_e32 v89, vcc, -1, v27, vcc
	v_add_co_u32_e32 v90, vcc, s16, v26
	global_load_dwordx2 v[88:89], v[88:89], off
	s_nop 0
	v_addc_co_u32_e32 v91, vcc, -1, v27, vcc
	s_mov_b32 s16, 0xffff4000
	global_load_dwordx2 v[90:91], v[90:91], off
	v_add_co_u32_e32 v92, vcc, s16, v26
	s_nop 1
	v_addc_co_u32_e32 v93, vcc, -1, v27, vcc
	global_load_dwordx2 v[92:93], v[92:93], off
	s_nop 0
	global_load_dwordx2 v[94:95], v[26:27], off
	ds_read_b128 v[76:79], v15
	ds_read_b128 v[6:9], v15 offset:16
	s_mov_b32 s16, 0xfffdc000
	s_add_i32 s0, s0, 8
	s_add_i32 s1, s1, 32
	s_cmpk_gt_u32 s0, 0x7b
	s_waitcnt vmcnt(7) lgkmcnt(1)
	v_pk_fma_f32 v[66:67], v[68:69], v[76:77], v[66:67] op_sel_hi:[1,0,1]
	s_waitcnt vmcnt(6)
	v_pk_fma_f32 v[66:67], v[80:81], v[76:77], v[66:67] op_sel:[0,1,0]
	v_mov_b32_e32 v76, v79
	s_waitcnt vmcnt(5)
	v_pk_fma_f32 v[66:67], v[82:83], v[78:79], v[66:67] op_sel_hi:[1,0,1]
	s_waitcnt vmcnt(4)
	v_pk_fma_f32 v[66:67], v[84:85], v[76:77], v[66:67] op_sel_hi:[1,0,1]
	ds_read_b128 v[76:79], v15 offset:512
	s_waitcnt lgkmcnt(0)
	v_pk_fma_f32 v[64:65], v[68:69], v[76:77], v[64:65] op_sel_hi:[1,0,1]
	s_nop 0
	v_pk_fma_f32 v[64:65], v[80:81], v[76:77], v[64:65] op_sel:[0,1,0]
	v_mov_b32_e32 v76, v79
	v_pk_fma_f32 v[64:65], v[82:83], v[78:79], v[64:65] op_sel_hi:[1,0,1]
	s_nop 0
	v_pk_fma_f32 v[64:65], v[84:85], v[76:77], v[64:65] op_sel_hi:[1,0,1]
	ds_read_b128 v[76:79], v15 offset:1024
	s_waitcnt lgkmcnt(0)
	v_pk_fma_f32 v[62:63], v[68:69], v[76:77], v[62:63] op_sel_hi:[1,0,1]
	s_nop 0
	v_pk_fma_f32 v[62:63], v[80:81], v[76:77], v[62:63] op_sel:[0,1,0]
	v_mov_b32_e32 v76, v79
	v_pk_fma_f32 v[62:63], v[82:83], v[78:79], v[62:63] op_sel_hi:[1,0,1]
	s_nop 0
	v_pk_fma_f32 v[62:63], v[84:85], v[76:77], v[62:63] op_sel_hi:[1,0,1]
	ds_read_b128 v[76:79], v15 offset:1536
	s_waitcnt lgkmcnt(0)
	v_pk_fma_f32 v[60:61], v[68:69], v[76:77], v[60:61] op_sel_hi:[1,0,1]
	s_nop 0
	v_pk_fma_f32 v[60:61], v[80:81], v[76:77], v[60:61] op_sel:[0,1,0]
	v_mov_b32_e32 v76, v79
	v_pk_fma_f32 v[60:61], v[82:83], v[78:79], v[60:61] op_sel_hi:[1,0,1]
	s_nop 0
	v_pk_fma_f32 v[60:61], v[84:85], v[76:77], v[60:61] op_sel_hi:[1,0,1]
	ds_read_b128 v[76:79], v15 offset:2048
	s_waitcnt lgkmcnt(0)
	v_pk_fma_f32 v[58:59], v[68:69], v[76:77], v[58:59] op_sel_hi:[1,0,1]
	s_nop 0
	v_pk_fma_f32 v[58:59], v[80:81], v[76:77], v[58:59] op_sel:[0,1,0]
	v_mov_b32_e32 v76, v79
	v_pk_fma_f32 v[58:59], v[82:83], v[78:79], v[58:59] op_sel_hi:[1,0,1]
	s_nop 0
	v_pk_fma_f32 v[58:59], v[84:85], v[76:77], v[58:59] op_sel_hi:[1,0,1]
	ds_read_b128 v[76:79], v15 offset:2560
	s_waitcnt lgkmcnt(0)
	v_pk_fma_f32 v[56:57], v[68:69], v[76:77], v[56:57] op_sel_hi:[1,0,1]
	s_nop 0
	v_pk_fma_f32 v[56:57], v[80:81], v[76:77], v[56:57] op_sel:[0,1,0]
	v_mov_b32_e32 v76, v79
	v_pk_fma_f32 v[56:57], v[82:83], v[78:79], v[56:57] op_sel_hi:[1,0,1]
	s_nop 0
	v_pk_fma_f32 v[56:57], v[84:85], v[76:77], v[56:57] op_sel_hi:[1,0,1]
	ds_read_b128 v[76:79], v15 offset:3072
	s_waitcnt lgkmcnt(0)
	v_pk_fma_f32 v[54:55], v[68:69], v[76:77], v[54:55] op_sel_hi:[1,0,1]
	s_nop 0
	v_pk_fma_f32 v[54:55], v[80:81], v[76:77], v[54:55] op_sel:[0,1,0]
	v_mov_b32_e32 v76, v79
	v_pk_fma_f32 v[54:55], v[82:83], v[78:79], v[54:55] op_sel_hi:[1,0,1]
	s_nop 0
	v_pk_fma_f32 v[54:55], v[84:85], v[76:77], v[54:55] op_sel_hi:[1,0,1]
	ds_read_b128 v[76:79], v15 offset:3584
	s_waitcnt lgkmcnt(0)
	v_pk_fma_f32 v[52:53], v[68:69], v[76:77], v[52:53] op_sel_hi:[1,0,1]
	s_nop 0
	v_pk_fma_f32 v[52:53], v[80:81], v[76:77], v[52:53] op_sel:[0,1,0]
	v_mov_b32_e32 v76, v79
	v_pk_fma_f32 v[52:53], v[82:83], v[78:79], v[52:53] op_sel_hi:[1,0,1]
	s_nop 0
	v_pk_fma_f32 v[52:53], v[84:85], v[76:77], v[52:53] op_sel_hi:[1,0,1]
	ds_read_b128 v[76:79], v15 offset:4096
	s_waitcnt lgkmcnt(0)
	v_pk_fma_f32 v[50:51], v[68:69], v[76:77], v[50:51] op_sel_hi:[1,0,1]
	s_nop 0
	v_pk_fma_f32 v[50:51], v[80:81], v[76:77], v[50:51] op_sel:[0,1,0]
	v_mov_b32_e32 v76, v79
	v_pk_fma_f32 v[50:51], v[82:83], v[78:79], v[50:51] op_sel_hi:[1,0,1]
	s_nop 0
	v_pk_fma_f32 v[50:51], v[84:85], v[76:77], v[50:51] op_sel_hi:[1,0,1]
	ds_read_b128 v[76:79], v15 offset:4608
	s_waitcnt lgkmcnt(0)
	v_pk_fma_f32 v[48:49], v[68:69], v[76:77], v[48:49] op_sel_hi:[1,0,1]
	s_nop 0
	v_pk_fma_f32 v[48:49], v[80:81], v[76:77], v[48:49] op_sel:[0,1,0]
	v_mov_b32_e32 v76, v79
	v_pk_fma_f32 v[48:49], v[82:83], v[78:79], v[48:49] op_sel_hi:[1,0,1]
	s_nop 0
	v_pk_fma_f32 v[48:49], v[84:85], v[76:77], v[48:49] op_sel_hi:[1,0,1]
	ds_read_b128 v[76:79], v15 offset:5120
	s_waitcnt lgkmcnt(0)
	v_pk_fma_f32 v[46:47], v[68:69], v[76:77], v[46:47] op_sel_hi:[1,0,1]
	s_nop 0
	v_pk_fma_f32 v[46:47], v[80:81], v[76:77], v[46:47] op_sel:[0,1,0]
	v_mov_b32_e32 v76, v79
	v_pk_fma_f32 v[46:47], v[82:83], v[78:79], v[46:47] op_sel_hi:[1,0,1]
	s_nop 0
	v_pk_fma_f32 v[46:47], v[84:85], v[76:77], v[46:47] op_sel_hi:[1,0,1]
	ds_read_b128 v[76:79], v15 offset:5632
	s_waitcnt lgkmcnt(0)
; #define LAS __attribute__((address_space(3)))
; __global__ void __launch_bounds__(NWAVES * 64, 2) mk_fwd(Args args) {
;     ...
;                     const float* wp = args.in[9] + ((size_t)lm * DM + k0) * (3 * DM) + col;
; #pragma unroll 2
;                     for (int k = 0; k < 128; k += 4) {
;                         const f32x2 wa = *(const f32x2*)(wp + (size_t)(k + 0) * (3 * DM)), wb = *(const f32x2*)(wp + (size_t)(k + 1) * (3 * DM));
;                         const f32x2 wc = *(const f32x2*)(wp + (size_t)(k + 2) * (3 * DM)), wd = *(const f32x2*)(wp + (size_t)(k + 3) * (3 * DM));
; #pragma unroll
;                         for (int r2 = 0; r2 < 20; ++r2) { const f32x4 cv = *(LAS const f32x4*)(cs + r2 * 128 + k);
;                             acc[r2] = wa * cv.x + acc[r2]; acc[r2] = wb * cv.y + acc[r2]; acc[r2] = wc * cv.z + acc[r2]; acc[r2] = wd * cv.w + acc[r2]; }
	v_pk_fma_f32 v[44:45], v[68:69], v[76:77], v[44:45] op_sel_hi:[1,0,1]
	s_nop 0
	v_pk_fma_f32 v[44:45], v[80:81], v[76:77], v[44:45] op_sel:[0,1,0]
	v_mov_b32_e32 v76, v79
	v_pk_fma_f32 v[44:45], v[82:83], v[78:79], v[44:45] op_sel_hi:[1,0,1]
	s_nop 0
	v_pk_fma_f32 v[44:45], v[84:85], v[76:77], v[44:45] op_sel_hi:[1,0,1]
	ds_read_b128 v[76:79], v15 offset:6144
	s_waitcnt lgkmcnt(0)
	v_pk_fma_f32 v[42:43], v[68:69], v[76:77], v[42:43] op_sel_hi:[1,0,1]
	s_nop 0
	v_pk_fma_f32 v[42:43], v[80:81], v[76:77], v[42:43] op_sel:[0,1,0]
	v_mov_b32_e32 v76, v79
	v_pk_fma_f32 v[42:43], v[82:83], v[78:79], v[42:43] op_sel_hi:[1,0,1]
	s_nop 0
	v_pk_fma_f32 v[42:43], v[84:85], v[76:77], v[42:43] op_sel_hi:[1,0,1]
	ds_read_b128 v[76:79], v15 offset:6656
	s_waitcnt lgkmcnt(0)
	v_pk_fma_f32 v[40:41], v[68:69], v[76:77], v[40:41] op_sel_hi:[1,0,1]
	s_nop 0
	v_pk_fma_f32 v[40:41], v[80:81], v[76:77], v[40:41] op_sel:[0,1,0]
	v_mov_b32_e32 v76, v79
	v_pk_fma_f32 v[40:41], v[82:83], v[78:79], v[40:41] op_sel_hi:[1,0,1]
	s_nop 0
	v_pk_fma_f32 v[40:41], v[84:85], v[76:77], v[40:41] op_sel_hi:[1,0,1]
	ds_read_b128 v[76:79], v15 offset:7168
	s_waitcnt lgkmcnt(0)
	v_pk_fma_f32 v[38:39], v[68:69], v[76:77], v[38:39] op_sel_hi:[1,0,1]
	s_nop 0
	v_pk_fma_f32 v[38:39], v[80:81], v[76:77], v[38:39] op_sel:[0,1,0]
	v_mov_b32_e32 v76, v79
	v_pk_fma_f32 v[38:39], v[82:83], v[78:79], v[38:39] op_sel_hi:[1,0,1]
	s_nop 0
	v_pk_fma_f32 v[38:39], v[84:85], v[76:77], v[38:39] op_sel_hi:[1,0,1]
	ds_read_b128 v[76:79], v15 offset:7680
	s_waitcnt lgkmcnt(0)
	v_pk_fma_f32 v[36:37], v[68:69], v[76:77], v[36:37] op_sel_hi:[1,0,1]
	s_nop 0
	v_pk_fma_f32 v[36:37], v[80:81], v[76:77], v[36:37] op_sel:[0,1,0]
	v_mov_b32_e32 v76, v79
	v_pk_fma_f32 v[36:37], v[82:83], v[78:79], v[36:37] op_sel_hi:[1,0,1]
	s_nop 0
	v_pk_fma_f32 v[36:37], v[84:85], v[76:77], v[36:37] op_sel_hi:[1,0,1]
	ds_read_b128 v[76:79], v15 offset:8192
	s_waitcnt lgkmcnt(0)
	v_pk_fma_f32 v[34:35], v[68:69], v[76:77], v[34:35] op_sel_hi:[1,0,1]
	s_nop 0
	v_pk_fma_f32 v[34:35], v[80:81], v[76:77], v[34:35] op_sel:[0,1,0]
	v_mov_b32_e32 v76, v79
	v_pk_fma_f32 v[34:35], v[82:83], v[78:79], v[34:35] op_sel_hi:[1,0,1]
	s_nop 0
	v_pk_fma_f32 v[34:35], v[84:85], v[76:77], v[34:35] op_sel_hi:[1,0,1]
	ds_read_b128 v[76:79], v15 offset:8704
	s_waitcnt lgkmcnt(0)
	v_pk_fma_f32 v[32:33], v[68:69], v[76:77], v[32:33] op_sel_hi:[1,0,1]
	s_nop 0
	v_pk_fma_f32 v[32:33], v[80:81], v[76:77], v[32:33] op_sel:[0,1,0]
	v_mov_b32_e32 v76, v79
	v_pk_fma_f32 v[32:33], v[82:83], v[78:79], v[32:33] op_sel_hi:[1,0,1]
	s_nop 0
	v_pk_fma_f32 v[32:33], v[84:85], v[76:77], v[32:33] op_sel_hi:[1,0,1]
	ds_read_b128 v[76:79], v15 offset:9216
	s_waitcnt lgkmcnt(0)
	v_pk_fma_f32 v[30:31], v[68:69], v[76:77], v[30:31] op_sel_hi:[1,0,1]
	s_nop 0
	v_pk_fma_f32 v[30:31], v[80:81], v[76:77], v[30:31] op_sel:[0,1,0]
	v_mov_b32_e32 v76, v79
	v_pk_fma_f32 v[30:31], v[82:83], v[78:79], v[30:31] op_sel_hi:[1,0,1]
	s_nop 0
	v_pk_fma_f32 v[30:31], v[84:85], v[76:77], v[30:31] op_sel_hi:[1,0,1]
	ds_read_b128 v[76:79], v15 offset:9728
	s_waitcnt lgkmcnt(0)
	v_pk_fma_f32 v[28:29], v[68:69], v[76:77], v[28:29] op_sel_hi:[1,0,1]
	s_nop 0
	v_pk_fma_f32 v[28:29], v[80:81], v[76:77], v[28:29] op_sel:[0,1,0]
	v_mov_b32_e32 v68, v79
	v_pk_fma_f32 v[28:29], v[82:83], v[78:79], v[28:29] op_sel_hi:[1,0,1]
	s_nop 0
	v_pk_fma_f32 v[28:29], v[84:85], v[68:69], v[28:29] op_sel_hi:[1,0,1]
	s_mov_b64 s[16:17], 0x60000
	v_lshl_add_u64 v[26:27], v[26:27], 0, s[16:17]
	s_waitcnt vmcnt(3)
	v_pk_fma_f32 v[66:67], v[88:89], v[6:7], v[66:67] op_sel_hi:[1,0,1]
	s_waitcnt vmcnt(2)
	v_pk_fma_f32 v[6:7], v[90:91], v[6:7], v[66:67] op_sel:[0,1,0]
	s_waitcnt vmcnt(1)
	v_pk_fma_f32 v[6:7], v[92:93], v[8:9], v[6:7] op_sel_hi:[1,0,1]
	v_mov_b32_e32 v8, v9
	s_waitcnt vmcnt(0)
	v_pk_fma_f32 v[66:67], v[94:95], v[8:9], v[6:7] op_sel_hi:[1,0,1]
	ds_read_b128 v[6:9], v15 offset:528
	s_waitcnt lgkmcnt(0)
	v_pk_fma_f32 v[64:65], v[88:89], v[6:7], v[64:65] op_sel_hi:[1,0,1]
	s_nop 0
	v_pk_fma_f32 v[6:7], v[90:91], v[6:7], v[64:65] op_sel:[0,1,0]
	s_nop 0
	v_pk_fma_f32 v[6:7], v[92:93], v[8:9], v[6:7] op_sel_hi:[1,0,1]
	v_mov_b32_e32 v8, v9
	v_pk_fma_f32 v[64:65], v[94:95], v[8:9], v[6:7] op_sel_hi:[1,0,1]
	ds_read_b128 v[6:9], v15 offset:1040
	s_waitcnt lgkmcnt(0)
	v_pk_fma_f32 v[62:63], v[88:89], v[6:7], v[62:63] op_sel_hi:[1,0,1]
	s_nop 0
	v_pk_fma_f32 v[6:7], v[90:91], v[6:7], v[62:63] op_sel:[0,1,0]
	s_nop 0
	v_pk_fma_f32 v[6:7], v[92:93], v[8:9], v[6:7] op_sel_hi:[1,0,1]
	v_mov_b32_e32 v8, v9
	v_pk_fma_f32 v[62:63], v[94:95], v[8:9], v[6:7] op_sel_hi:[1,0,1]
	ds_read_b128 v[6:9], v15 offset:1552
	s_waitcnt lgkmcnt(0)
	v_pk_fma_f32 v[60:61], v[88:89], v[6:7], v[60:61] op_sel_hi:[1,0,1]
	s_nop 0
	v_pk_fma_f32 v[6:7], v[90:91], v[6:7], v[60:61] op_sel:[0,1,0]
	s_nop 0
	v_pk_fma_f32 v[6:7], v[92:93], v[8:9], v[6:7] op_sel_hi:[1,0,1]
	v_mov_b32_e32 v8, v9
	v_pk_fma_f32 v[60:61], v[94:95], v[8:9], v[6:7] op_sel_hi:[1,0,1]
	ds_read_b128 v[6:9], v15 offset:2064
	s_waitcnt lgkmcnt(0)
	v_pk_fma_f32 v[58:59], v[88:89], v[6:7], v[58:59] op_sel_hi:[1,0,1]
	s_nop 0
	v_pk_fma_f32 v[6:7], v[90:91], v[6:7], v[58:59] op_sel:[0,1,0]
	s_nop 0
	v_pk_fma_f32 v[6:7], v[92:93], v[8:9], v[6:7] op_sel_hi:[1,0,1]
	v_mov_b32_e32 v8, v9
	v_pk_fma_f32 v[58:59], v[94:95], v[8:9], v[6:7] op_sel_hi:[1,0,1]
	ds_read_b128 v[6:9], v15 offset:2576
	s_waitcnt lgkmcnt(0)
	v_pk_fma_f32 v[56:57], v[88:89], v[6:7], v[56:57] op_sel_hi:[1,0,1]
	s_nop 0
	v_pk_fma_f32 v[6:7], v[90:91], v[6:7], v[56:57] op_sel:[0,1,0]
	s_nop 0
	v_pk_fma_f32 v[6:7], v[92:93], v[8:9], v[6:7] op_sel_hi:[1,0,1]
	v_mov_b32_e32 v8, v9
	v_pk_fma_f32 v[56:57], v[94:95], v[8:9], v[6:7] op_sel_hi:[1,0,1]
	ds_read_b128 v[6:9], v15 offset:3088
	s_waitcnt lgkmcnt(0)
; #define LAS __attribute__((address_space(3)))
; __global__ void __launch_bounds__(NWAVES * 64, 2) mk_fwd(Args args) {
;     ...
;                     const float* wp = args.in[9] + ((size_t)lm * DM + k0) * (3 * DM) + col;
; #pragma unroll 2
;                     for (int k = 0; k < 128; k += 4) {
;                         const f32x2 wa = *(const f32x2*)(wp + (size_t)(k + 0) * (3 * DM)), wb = *(const f32x2*)(wp + (size_t)(k + 1) * (3 * DM));
;                         const f32x2 wc = *(const f32x2*)(wp + (size_t)(k + 2) * (3 * DM)), wd = *(const f32x2*)(wp + (size_t)(k + 3) * (3 * DM));
; #pragma unroll
;                         for (int r2 = 0; r2 < 20; ++r2) { const f32x4 cv = *(LAS const f32x4*)(cs + r2 * 128 + k);
;                             acc[r2] = wa * cv.x + acc[r2]; acc[r2] = wb * cv.y + acc[r2]; acc[r2] = wc * cv.z + acc[r2]; acc[r2] = wd * cv.w + acc[r2]; }
	v_pk_fma_f32 v[54:55], v[88:89], v[6:7], v[54:55] op_sel_hi:[1,0,1]
	s_nop 0
	v_pk_fma_f32 v[6:7], v[90:91], v[6:7], v[54:55] op_sel:[0,1,0]
	s_nop 0
	v_pk_fma_f32 v[6:7], v[92:93], v[8:9], v[6:7] op_sel_hi:[1,0,1]
	v_mov_b32_e32 v8, v9
	v_pk_fma_f32 v[54:55], v[94:95], v[8:9], v[6:7] op_sel_hi:[1,0,1]
	ds_read_b128 v[6:9], v15 offset:3600
	s_waitcnt lgkmcnt(0)
	v_pk_fma_f32 v[52:53], v[88:89], v[6:7], v[52:53] op_sel_hi:[1,0,1]
	s_nop 0
	v_pk_fma_f32 v[6:7], v[90:91], v[6:7], v[52:53] op_sel:[0,1,0]
	s_nop 0
	v_pk_fma_f32 v[6:7], v[92:93], v[8:9], v[6:7] op_sel_hi:[1,0,1]
	v_mov_b32_e32 v8, v9
	v_pk_fma_f32 v[52:53], v[94:95], v[8:9], v[6:7] op_sel_hi:[1,0,1]
	ds_read_b128 v[6:9], v15 offset:4112
	s_waitcnt lgkmcnt(0)
	v_pk_fma_f32 v[50:51], v[88:89], v[6:7], v[50:51] op_sel_hi:[1,0,1]
	s_nop 0
	v_pk_fma_f32 v[6:7], v[90:91], v[6:7], v[50:51] op_sel:[0,1,0]
	s_nop 0
	v_pk_fma_f32 v[6:7], v[92:93], v[8:9], v[6:7] op_sel_hi:[1,0,1]
	v_mov_b32_e32 v8, v9
	v_pk_fma_f32 v[50:51], v[94:95], v[8:9], v[6:7] op_sel_hi:[1,0,1]
	ds_read_b128 v[6:9], v15 offset:4624
	s_waitcnt lgkmcnt(0)
	v_pk_fma_f32 v[48:49], v[88:89], v[6:7], v[48:49] op_sel_hi:[1,0,1]
	s_nop 0
	v_pk_fma_f32 v[6:7], v[90:91], v[6:7], v[48:49] op_sel:[0,1,0]
	s_nop 0
	v_pk_fma_f32 v[6:7], v[92:93], v[8:9], v[6:7] op_sel_hi:[1,0,1]
	v_mov_b32_e32 v8, v9
	v_pk_fma_f32 v[48:49], v[94:95], v[8:9], v[6:7] op_sel_hi:[1,0,1]
	ds_read_b128 v[6:9], v15 offset:5136
	s_waitcnt lgkmcnt(0)
	v_pk_fma_f32 v[46:47], v[88:89], v[6:7], v[46:47] op_sel_hi:[1,0,1]
	s_nop 0
	v_pk_fma_f32 v[6:7], v[90:91], v[6:7], v[46:47] op_sel:[0,1,0]
	s_nop 0
	v_pk_fma_f32 v[6:7], v[92:93], v[8:9], v[6:7] op_sel_hi:[1,0,1]
	v_mov_b32_e32 v8, v9
	v_pk_fma_f32 v[46:47], v[94:95], v[8:9], v[6:7] op_sel_hi:[1,0,1]
	ds_read_b128 v[6:9], v15 offset:5648
	s_waitcnt lgkmcnt(0)
	v_pk_fma_f32 v[44:45], v[88:89], v[6:7], v[44:45] op_sel_hi:[1,0,1]
	s_nop 0
	v_pk_fma_f32 v[6:7], v[90:91], v[6:7], v[44:45] op_sel:[0,1,0]
	s_nop 0
	v_pk_fma_f32 v[6:7], v[92:93], v[8:9], v[6:7] op_sel_hi:[1,0,1]
	v_mov_b32_e32 v8, v9
	v_pk_fma_f32 v[44:45], v[94:95], v[8:9], v[6:7] op_sel_hi:[1,0,1]
	ds_read_b128 v[6:9], v15 offset:6160
	s_waitcnt lgkmcnt(0)
	v_pk_fma_f32 v[42:43], v[88:89], v[6:7], v[42:43] op_sel_hi:[1,0,1]
	s_nop 0
	v_pk_fma_f32 v[6:7], v[90:91], v[6:7], v[42:43] op_sel:[0,1,0]
	s_nop 0
	v_pk_fma_f32 v[6:7], v[92:93], v[8:9], v[6:7] op_sel_hi:[1,0,1]
	v_mov_b32_e32 v8, v9
	v_pk_fma_f32 v[42:43], v[94:95], v[8:9], v[6:7] op_sel_hi:[1,0,1]
	ds_read_b128 v[6:9], v15 offset:6672
	s_waitcnt lgkmcnt(0)
	v_pk_fma_f32 v[40:41], v[88:89], v[6:7], v[40:41] op_sel_hi:[1,0,1]
	s_nop 0
	v_pk_fma_f32 v[6:7], v[90:91], v[6:7], v[40:41] op_sel:[0,1,0]
	s_nop 0
	v_pk_fma_f32 v[6:7], v[92:93], v[8:9], v[6:7] op_sel_hi:[1,0,1]
	v_mov_b32_e32 v8, v9
	v_pk_fma_f32 v[40:41], v[94:95], v[8:9], v[6:7] op_sel_hi:[1,0,1]
	ds_read_b128 v[6:9], v15 offset:7184
	s_waitcnt lgkmcnt(0)
	v_pk_fma_f32 v[38:39], v[88:89], v[6:7], v[38:39] op_sel_hi:[1,0,1]
	s_nop 0
	v_pk_fma_f32 v[6:7], v[90:91], v[6:7], v[38:39] op_sel:[0,1,0]
	s_nop 0
	v_pk_fma_f32 v[6:7], v[92:93], v[8:9], v[6:7] op_sel_hi:[1,0,1]
	v_mov_b32_e32 v8, v9
	v_pk_fma_f32 v[38:39], v[94:95], v[8:9], v[6:7] op_sel_hi:[1,0,1]
	ds_read_b128 v[6:9], v15 offset:7696
	s_waitcnt lgkmcnt(0)
	v_pk_fma_f32 v[36:37], v[88:89], v[6:7], v[36:37] op_sel_hi:[1,0,1]
	s_nop 0
	v_pk_fma_f32 v[6:7], v[90:91], v[6:7], v[36:37] op_sel:[0,1,0]
	s_nop 0
	v_pk_fma_f32 v[6:7], v[92:93], v[8:9], v[6:7] op_sel_hi:[1,0,1]
	v_mov_b32_e32 v8, v9
	v_pk_fma_f32 v[36:37], v[94:95], v[8:9], v[6:7] op_sel_hi:[1,0,1]
	ds_read_b128 v[6:9], v15 offset:8208
	s_waitcnt lgkmcnt(0)
	v_pk_fma_f32 v[34:35], v[88:89], v[6:7], v[34:35] op_sel_hi:[1,0,1]
	s_nop 0
	v_pk_fma_f32 v[6:7], v[90:91], v[6:7], v[34:35] op_sel:[0,1,0]
	s_nop 0
	v_pk_fma_f32 v[6:7], v[92:93], v[8:9], v[6:7] op_sel_hi:[1,0,1]
	v_mov_b32_e32 v8, v9
	v_pk_fma_f32 v[34:35], v[94:95], v[8:9], v[6:7] op_sel_hi:[1,0,1]
	ds_read_b128 v[6:9], v15 offset:8720
	s_waitcnt lgkmcnt(0)
	v_pk_fma_f32 v[32:33], v[88:89], v[6:7], v[32:33] op_sel_hi:[1,0,1]
	s_nop 0
	v_pk_fma_f32 v[6:7], v[90:91], v[6:7], v[32:33] op_sel:[0,1,0]
	s_nop 0
	v_pk_fma_f32 v[6:7], v[92:93], v[8:9], v[6:7] op_sel_hi:[1,0,1]
	v_mov_b32_e32 v8, v9
	v_pk_fma_f32 v[32:33], v[94:95], v[8:9], v[6:7] op_sel_hi:[1,0,1]
	ds_read_b128 v[6:9], v15 offset:9232
	s_waitcnt lgkmcnt(0)
	v_pk_fma_f32 v[30:31], v[88:89], v[6:7], v[30:31] op_sel_hi:[1,0,1]
	s_nop 0
	v_pk_fma_f32 v[6:7], v[90:91], v[6:7], v[30:31] op_sel:[0,1,0]
	s_nop 0
	v_pk_fma_f32 v[6:7], v[92:93], v[8:9], v[6:7] op_sel_hi:[1,0,1]
	v_mov_b32_e32 v8, v9
	v_pk_fma_f32 v[30:31], v[94:95], v[8:9], v[6:7] op_sel_hi:[1,0,1]
	ds_read_b128 v[6:9], v15 offset:9744
	s_waitcnt lgkmcnt(0)
	v_pk_fma_f32 v[28:29], v[88:89], v[6:7], v[28:29] op_sel_hi:[1,0,1]
	s_nop 0
	v_pk_fma_f32 v[6:7], v[90:91], v[6:7], v[28:29] op_sel:[0,1,0]
	s_nop 0
	v_pk_fma_f32 v[6:7], v[92:93], v[8:9], v[6:7] op_sel_hi:[1,0,1]
	v_mov_b32_e32 v8, v9
	v_pk_fma_f32 v[28:29], v[94:95], v[8:9], v[6:7] op_sel_hi:[1,0,1]
	s_cbranch_scc0 .LBB0_29
; __global__ void __launch_bounds__(NWAVES * 64, 2) mk_fwd(Args args) {
;     ...
;                 }
;                 float* mp = modp + ((size_t)(lm * 11 + sl) * 20) * (3 * DM) + col;
; #pragma unroll
;                 for (int r2 = 0; r2 < 20; ++r2) *(f32x2*)(mp + (size_t)r2 * (3 * DM)) = acc[r2];
;             }
	s_add_i32 s40, s40, s36
	s_add_i32 s38, s38, s39
	s_cmp_gt_i32 s40, 31
	s_cbranch_scc0 .LBB0_18
	s_mul_i32 s37, s37, 11
	s_sext_i32_i8 s0, s37
	s_add_i32 s0, s35, s0
	s_mul_hi_i32 s1, s0, 0xf0000
	s_mul_i32 s0, s0, 0xf0000
	s_add_u32 s0, s15, s0
	s_addc_u32 s1, s28, s1
	v_lshl_add_u64 v[6:7], v[22:23], 2, s[0:1]
	v_add_co_u32_e32 v8, vcc, 0xc000, v6
	global_store_dwordx2 v[6:7], v[66:67], off
	s_nop 0
	v_addc_co_u32_e32 v9, vcc, 0, v7, vcc
	global_store_dwordx2 v[8:9], v[64:65], off
	v_add_co_u32_e32 v8, vcc, 0x18000, v6
	s_add_i32 s34, s34, s25
	s_nop 0
	v_addc_co_u32_e32 v9, vcc, 0, v7, vcc
	global_store_dwordx2 v[8:9], v[62:63], off
	v_add_co_u32_e32 v8, vcc, 0x24000, v6
	s_cmpk_gt_i32 s34, 0xff
	s_nop 0
	v_addc_co_u32_e32 v9, vcc, 0, v7, vcc
	global_store_dwordx2 v[8:9], v[60:61], off
	v_add_co_u32_e32 v8, vcc, 0x30000, v6
	s_nop 1
	v_addc_co_u32_e32 v9, vcc, 0, v7, vcc
	global_store_dwordx2 v[8:9], v[58:59], off
	v_add_co_u32_e32 v8, vcc, 0x3c000, v6
	s_nop 1
	v_addc_co_u32_e32 v9, vcc, 0, v7, vcc
	global_store_dwordx2 v[8:9], v[56:57], off
	v_add_co_u32_e32 v8, vcc, 0x48000, v6
	s_nop 1
	v_addc_co_u32_e32 v9, vcc, 0, v7, vcc
	global_store_dwordx2 v[8:9], v[54:55], off
	v_add_co_u32_e32 v8, vcc, 0x54000, v6
	s_nop 1
	v_addc_co_u32_e32 v9, vcc, 0, v7, vcc
	global_store_dwordx2 v[8:9], v[52:53], off
	v_add_co_u32_e32 v8, vcc, 0x60000, v6
	s_nop 1
	v_addc_co_u32_e32 v9, vcc, 0, v7, vcc
	global_store_dwordx2 v[8:9], v[50:51], off
	v_add_co_u32_e32 v8, vcc, 0x6c000, v6
	s_nop 1
	v_addc_co_u32_e32 v9, vcc, 0, v7, vcc
	global_store_dwordx2 v[8:9], v[48:49], off
	v_add_co_u32_e32 v8, vcc, 0x78000, v6
	s_nop 1
	v_addc_co_u32_e32 v9, vcc, 0, v7, vcc
	global_store_dwordx2 v[8:9], v[46:47], off
	v_add_co_u32_e32 v8, vcc, 0x84000, v6
	s_nop 1
	v_addc_co_u32_e32 v9, vcc, 0, v7, vcc
	global_store_dwordx2 v[8:9], v[44:45], off
	v_add_co_u32_e32 v8, vcc, 0x90000, v6
	s_nop 1
	v_addc_co_u32_e32 v9, vcc, 0, v7, vcc
	global_store_dwordx2 v[8:9], v[42:43], off
	v_add_co_u32_e32 v8, vcc, 0x9c000, v6
	s_nop 1
	v_addc_co_u32_e32 v9, vcc, 0, v7, vcc
	global_store_dwordx2 v[8:9], v[40:41], off
	v_add_co_u32_e32 v8, vcc, 0xa8000, v6
	s_nop 1
	v_addc_co_u32_e32 v9, vcc, 0, v7, vcc
	global_store_dwordx2 v[8:9], v[38:39], off
	v_add_co_u32_e32 v8, vcc, 0xb4000, v6
	s_nop 1
	v_addc_co_u32_e32 v9, vcc, 0, v7, vcc
	global_store_dwordx2 v[8:9], v[36:37], off
	v_add_co_u32_e32 v8, vcc, 0xc0000, v6
	s_nop 1
	v_addc_co_u32_e32 v9, vcc, 0, v7, vcc
	global_store_dwordx2 v[8:9], v[34:35], off
	v_add_co_u32_e32 v8, vcc, 0xcc000, v6
	s_nop 1
	v_addc_co_u32_e32 v9, vcc, 0, v7, vcc
	global_store_dwordx2 v[8:9], v[32:33], off
	v_add_co_u32_e32 v8, vcc, 0xd8000, v6
	s_nop 1
	v_addc_co_u32_e32 v9, vcc, 0, v7, vcc
	v_add_co_u32_e32 v6, vcc, 0xe4000, v6
	global_store_dwordx2 v[8:9], v[30:31], off
	s_nop 0
	v_addc_co_u32_e32 v7, vcc, 0, v7, vcc
	global_store_dwordx2 v[6:7], v[28:29], off
	s_cbranch_scc0 .LBB0_17
